# prep waves: next chunk's global prefetch issued right after step A (cover = steps B+C+E instead of E only)
# speedup vs baseline: 1.0044x; 1.0044x over previous
.LBB0_787:
	global_load_dwordx4 v[108:111], v[114:115], off
	s_add_i32 s34, s6, 2
	s_cmp_ge_u32 s34, s43
	s_cbranch_scc1 .LBB0_784
	s_bitcmp1_b32 s34, 0
	s_cselect_b32 s34, 0xe180, 0
	s_add_i32 s34, s34, 16
	v_lshlrev_b32_e32 v136, 2, v118
	v_add3_u32 v142, s34, v136, v149
	s_waitcnt vmcnt(8)
	v_lshlrev_b32_e32 v136, 16, v72
	v_and_b32_e32 v137, 0xffff0000, v72
	v_lshlrev_b32_e32 v138, 16, v68
	v_and_b32_e32 v139, 0xffff0000, v68
	v_pk_add_f32 v[136:137], v[136:137], v[138:139] neg_lo:[0,1] neg_hi:[0,1]
	v_lshlrev_b32_e32 v140, 16, v69
	v_pk_fma_f32 v[136:137], v[4:5], v[136:137], v[138:139]
	v_lshlrev_b32_e32 v138, 16, v73
	v_and_b32_e32 v139, 0xffff0000, v73
	v_and_b32_e32 v141, 0xffff0000, v69
	v_pk_add_f32 v[138:139], v[138:139], v[140:141] neg_lo:[0,1] neg_hi:[0,1]
	s_waitcnt vmcnt(2)
	v_lshlrev_b32_e32 v145, 16, v96
	v_pk_fma_f32 v[138:139], v[6:7], v[138:139], v[140:141]
	ds_write_b128 v142, v[136:139] offset:32768
	v_lshlrev_b32_e32 v136, 16, v74
	v_and_b32_e32 v137, 0xffff0000, v74
	v_lshlrev_b32_e32 v138, 16, v70
	v_and_b32_e32 v139, 0xffff0000, v70
	v_pk_add_f32 v[136:137], v[136:137], v[138:139] neg_lo:[0,1] neg_hi:[0,1]
	v_lshlrev_b32_e32 v140, 16, v71
	v_pk_fma_f32 v[136:137], v[8:9], v[136:137], v[138:139]
	v_lshlrev_b32_e32 v138, 16, v75
	v_and_b32_e32 v139, 0xffff0000, v75
	v_and_b32_e32 v141, 0xffff0000, v71
	v_pk_add_f32 v[138:139], v[138:139], v[140:141] neg_lo:[0,1] neg_hi:[0,1]
	v_lshlrev_b32_e32 v143, 16, v94
	v_pk_fma_f32 v[138:139], v[10:11], v[138:139], v[140:141]
	ds_write_b128 v142, v[136:139] offset:32784
	v_lshlrev_b32_e32 v136, 16, v80
	v_and_b32_e32 v137, 0xffff0000, v80
	v_lshlrev_b32_e32 v138, 16, v76
	v_and_b32_e32 v139, 0xffff0000, v76
	v_pk_add_f32 v[136:137], v[136:137], v[138:139] neg_lo:[0,1] neg_hi:[0,1]
	v_lshlrev_b32_e32 v140, 16, v77
	v_pk_fma_f32 v[136:137], v[44:45], v[136:137], v[138:139]
	v_lshlrev_b32_e32 v138, 16, v81
	v_and_b32_e32 v139, 0xffff0000, v81
	v_and_b32_e32 v141, 0xffff0000, v77
	v_pk_add_f32 v[138:139], v[138:139], v[140:141] neg_lo:[0,1] neg_hi:[0,1]
	v_lshlrev_b32_e32 v144, 16, v98
	v_pk_fma_f32 v[138:139], v[46:47], v[138:139], v[140:141]
	ds_write_b128 v142, v[136:139] offset:24576
	v_lshlrev_b32_e32 v136, 16, v82
	v_and_b32_e32 v137, 0xffff0000, v82
	v_lshlrev_b32_e32 v138, 16, v78
	v_and_b32_e32 v139, 0xffff0000, v78
	v_pk_add_f32 v[136:137], v[136:137], v[138:139] neg_lo:[0,1] neg_hi:[0,1]
	v_lshlrev_b32_e32 v140, 16, v79
	v_pk_fma_f32 v[136:137], v[48:49], v[136:137], v[138:139]
	v_lshlrev_b32_e32 v138, 16, v83
	v_and_b32_e32 v139, 0xffff0000, v83
	v_and_b32_e32 v141, 0xffff0000, v79
	v_pk_add_f32 v[138:139], v[138:139], v[140:141] neg_lo:[0,1] neg_hi:[0,1]
	v_sub_f32_e32 v144, v144, v143
	v_pk_fma_f32 v[138:139], v[50:51], v[138:139], v[140:141]
	ds_write_b128 v142, v[136:139] offset:24592
	v_lshlrev_b32_e32 v136, 16, v88
	v_and_b32_e32 v137, 0xffff0000, v88
	v_lshlrev_b32_e32 v138, 16, v84
	v_and_b32_e32 v139, 0xffff0000, v84
	v_pk_add_f32 v[136:137], v[136:137], v[138:139] neg_lo:[0,1] neg_hi:[0,1]
	v_lshlrev_b32_e32 v140, 16, v85
	v_pk_fma_f32 v[136:137], v[52:53], v[136:137], v[138:139]
	v_lshlrev_b32_e32 v138, 16, v89
	v_and_b32_e32 v139, 0xffff0000, v89
	v_and_b32_e32 v141, 0xffff0000, v85
	v_pk_add_f32 v[138:139], v[138:139], v[140:141] neg_lo:[0,1] neg_hi:[0,1]
	v_fmac_f32_e32 v143, v16, v144
	v_pk_fma_f32 v[138:139], v[54:55], v[138:139], v[140:141]
	ds_write_b128 v142, v[136:139] offset:40960
	v_lshlrev_b32_e32 v136, 16, v90
	v_and_b32_e32 v137, 0xffff0000, v90
	v_lshlrev_b32_e32 v138, 16, v86
	v_and_b32_e32 v139, 0xffff0000, v86
	v_pk_add_f32 v[136:137], v[136:137], v[138:139] neg_lo:[0,1] neg_hi:[0,1]
	v_lshlrev_b32_e32 v140, 16, v87
	v_pk_fma_f32 v[136:137], v[56:57], v[136:137], v[138:139]
	v_lshlrev_b32_e32 v138, 16, v91
	v_and_b32_e32 v139, 0xffff0000, v91
	v_and_b32_e32 v141, 0xffff0000, v87
	v_pk_add_f32 v[138:139], v[138:139], v[140:141] neg_lo:[0,1] neg_hi:[0,1]
	v_add3_u32 v214, s34, v155, v120
	v_pk_fma_f32 v[138:139], v[58:59], v[138:139], v[140:141]
	ds_write_b128 v142, v[136:139] offset:40976
	v_and_b32_e32 v140, 0xffff0000, v95
	v_and_b32_e32 v136, 0xffff0000, v99
	v_sub_f32_e32 v136, v136, v140
	v_fmac_f32_e32 v140, v19, v136
	v_lshlrev_b32_e32 v141, 16, v95
	v_lshlrev_b32_e32 v136, 16, v99
	v_sub_f32_e32 v136, v136, v141
	v_fmac_f32_e32 v141, v18, v136
	v_and_b32_e32 v142, 0xffff0000, v94
	v_and_b32_e32 v136, 0xffff0000, v98
	v_sub_f32_e32 v136, v136, v142
	v_fmac_f32_e32 v142, v17, v136
	v_and_b32_e32 v136, 0xffff0000, v93
	v_and_b32_e32 v137, 0xffff0000, v97
	v_sub_f32_e32 v137, v137, v136
	v_fmac_f32_e32 v136, v15, v137
	v_lshlrev_b32_e32 v137, 16, v93
	v_lshlrev_b32_e32 v138, 16, v97
	v_sub_f32_e32 v138, v138, v137
	v_fmac_f32_e32 v137, v14, v138
	v_and_b32_e32 v138, 0xffff0000, v92
	v_and_b32_e32 v139, 0xffff0000, v96
	v_sub_f32_e32 v139, v139, v138
	v_fmac_f32_e32 v138, v13, v139
	v_lshlrev_b32_e32 v139, 16, v92
	v_sub_f32_e32 v145, v145, v139
	v_fmac_f32_e32 v139, v12, v145
	v_add_f32_e32 v139, v139, v139
	v_add_f32_e32 v138, v138, v138
	v_mul_f32_e32 v139, 0x3fb8aa3b, v139
	v_mul_f32_e32 v138, 0x3fb8aa3b, v138
	v_add_f32_e32 v137, v137, v137
	v_add_f32_e32 v136, v136, v136
	v_exp_f32_e32 v139, v139
	v_exp_f32_e32 v138, v138
	v_mul_f32_e32 v137, 0x3fb8aa3b, v137
	v_mul_f32_e32 v136, 0x3fb8aa3b, v136
	v_exp_f32_e32 v137, v137
	v_exp_f32_e32 v136, v136
	v_add_f32_e32 v139, 1.0, v139
	v_add_f32_e32 v138, 1.0, v138
	v_add_f32_e32 v145, 1.0, v137
	v_add_f32_e32 v146, 1.0, v136
	v_rcp_f32_e64 v137, -v138
	v_rcp_f32_e64 v136, -v139
	v_rcp_f32_e64 v139, -v146
	v_add_f32_e32 v141, v141, v141
	v_add_f32_e32 v140, v140, v140
	v_pk_fma_f32 v[136:137], v[136:137], 2.0, 1.0 op_sel_hi:[1,0,0]
	v_mul_f32_e32 v141, 0x3fb8aa3b, v141
	v_bfe_u32 v146, v137, 16, 1
	v_bfe_u32 v147, v136, 16, 1
	v_add3_u32 v147, v136, v147, s89
	v_add3_u32 v146, v137, v146, s89
	v_add_f32_e32 v136, v143, v143
	v_add_f32_e32 v137, v142, v142
	v_mul_f32_e32 v136, 0x3fb8aa3b, v136
	v_mul_f32_e32 v137, 0x3fb8aa3b, v137
	v_mul_f32_e32 v140, 0x3fb8aa3b, v140
	v_exp_f32_e32 v136, v136
	v_exp_f32_e32 v137, v137
	v_exp_f32_e32 v141, v141
	v_exp_f32_e32 v140, v140
	v_rcp_f32_e64 v138, -v145
	v_add_f32_e32 v136, 1.0, v136
	v_add_f32_e32 v137, 1.0, v137
	v_add_f32_e32 v142, 1.0, v141
	v_add_f32_e32 v140, 1.0, v140
	v_rcp_f32_e64 v137, -v137
	v_rcp_f32_e64 v136, -v136
	v_rcp_f32_e64 v141, -v140
	v_rcp_f32_e64 v140, -v142
	v_pk_fma_f32 v[138:139], v[138:139], 2.0, 1.0 op_sel_hi:[1,0,0]
	v_pk_fma_f32 v[136:137], v[136:137], 2.0, 1.0 op_sel_hi:[1,0,0]
	v_bfe_u32 v144, v139, 16, 1
	v_bfe_u32 v145, v138, 16, 1
	v_add3_u32 v142, v138, v145, s89
	v_add3_u32 v143, v139, v144, s89
	v_pk_fma_f32 v[138:139], v[140:141], 2.0, 1.0 op_sel_hi:[1,0,0]
	v_bfe_u32 v144, v137, 16, 1
	v_bfe_u32 v140, v139, 16, 1
	v_bfe_u32 v141, v138, 16, 1
	v_bfe_u32 v145, v136, 16, 1
	v_add3_u32 v136, v136, v145, s89
	v_add3_u32 v137, v137, v144, s89
	v_add3_u32 v138, v138, v141, s89
	v_add3_u32 v139, v139, v140, s89
	v_perm_b32 v139, v139, v138, s90
	v_perm_b32 v138, v137, v136, s90
	v_perm_b32 v137, v143, v142, s90
	v_perm_b32 v136, v146, v147, s90
	ds_write_b128 v121, v[136:139]
	s_waitcnt vmcnt(1)
	v_lshlrev_b32_e32 v142, 16, v104
	v_lshlrev_b32_e32 v140, 16, v105
	v_and_b32_e32 v143, 0xffff0000, v104
	v_and_b32_e32 v141, 0xffff0000, v105
	v_lshlrev_b32_e32 v136, 16, v100
	v_lshlrev_b32_e32 v138, 16, v101
	v_and_b32_e32 v137, 0xffff0000, v100
	v_and_b32_e32 v139, 0xffff0000, v101
	v_sub_f32_e32 v141, v141, v139
	v_sub_f32_e32 v140, v140, v138
	v_sub_f32_e32 v143, v143, v137
	v_sub_f32_e32 v142, v142, v136
	v_pk_fma_f32 v[136:137], v[60:61], v[142:143], v[136:137]
	v_pk_fma_f32 v[138:139], v[62:63], v[140:141], v[138:139]
	v_bfe_u32 v142, v137, 16, 1
	v_bfe_u32 v140, v139, 16, 1
	v_bfe_u32 v141, v138, 16, 1
	v_bfe_u32 v143, v136, 16, 1
	v_add3_u32 v144, v136, v143, s89
	v_add3_u32 v145, v137, v142, s89
	v_add3_u32 v146, v138, v141, s89
	v_add3_u32 v147, v139, v140, s89
	v_lshlrev_b32_e32 v142, 16, v106
	v_lshlrev_b32_e32 v140, 16, v107
	v_and_b32_e32 v143, 0xffff0000, v106
	v_and_b32_e32 v141, 0xffff0000, v107
	v_lshlrev_b32_e32 v136, 16, v102
	v_lshlrev_b32_e32 v138, 16, v103
	v_and_b32_e32 v137, 0xffff0000, v102
	v_and_b32_e32 v139, 0xffff0000, v103
	v_sub_f32_e32 v141, v141, v139
	v_sub_f32_e32 v140, v140, v138
	v_sub_f32_e32 v143, v143, v137
	v_sub_f32_e32 v142, v142, v136
	v_pk_fma_f32 v[136:137], v[64:65], v[142:143], v[136:137]
	v_pk_fma_f32 v[138:139], v[66:67], v[140:141], v[138:139]
	v_bfe_u32 v142, v137, 16, 1
	v_bfe_u32 v140, v139, 16, 1
	v_bfe_u32 v141, v138, 16, 1
	v_bfe_u32 v143, v136, 16, 1
	v_add3_u32 v136, v136, v143, s89
	v_add3_u32 v137, v137, v142, s89
	v_add3_u32 v138, v138, v141, s89
	v_add3_u32 v139, v139, v140, s89
	v_perm_b32 v139, v139, v138, s90
	v_perm_b32 v138, v137, v136, s90
	v_perm_b32 v137, v147, v146, s90
	v_perm_b32 v136, v145, v144, s90
	ds_write_b128 v159, v[136:139]
	s_add_i32 s35, s6, 3
	s_cmp_ge_u32 s35, s43
	s_cbranch_scc1 .Lpf_skip
	s_waitcnt vmcnt(0)
	v_lshl_add_u64 v[84:85], v[128:129], 0, s[4:5]
	v_add_co_u32_e32 v72, vcc, 0x239a5000, v84
	v_lshl_add_u64 v[92:93], v[130:131], 0, s[4:5]
	s_nop 0
	v_addc_co_u32_e32 v73, vcc, 0, v85, vcc
	v_add_co_u32_e32 v74, vcc, 0x239a3000, v84
	v_lshl_add_u64 v[80:81], v[132:133], 0, s[4:5]
	s_nop 0
	v_addc_co_u32_e32 v75, vcc, 0, v85, vcc
	v_add_co_u32_e32 v88, vcc, 0x239a4000, v84
	v_lshl_add_u64 v[86:87], v[134:135], 0, s[4:5]
	s_nop 0
	v_addc_co_u32_e32 v89, vcc, 0, v85, vcc
	v_add_co_u32_e32 v96, vcc, 0x239a6000, v92
	global_load_dwordx4 v[68:71], v[72:73], off
	global_load_dwordx4 v[76:79], v[72:73], off offset:2048
	v_addc_co_u32_e32 v97, vcc, 0, v93, vcc
	v_add_co_u32_e32 v104, vcc, 0x239a4000, v92
	global_load_dwordx4 v[72:75], v[74:75], off offset:1792
	s_nop 0
	global_load_dwordx4 v[80:83], v[80:81], off
	v_addc_co_u32_e32 v105, vcc, 0, v93, vcc
	global_load_dwordx4 v[84:87], v[86:87], off
	s_nop 0
	global_load_dwordx4 v[88:91], v[88:89], off offset:1792
	s_nop 0
	global_load_dwordx4 v[92:95], v[96:97], off offset:2048
	global_load_dwordx4 v[100:103], v[96:97], off offset:2176
	s_nop 0
	global_load_dwordx4 v[96:99], v[104:105], off offset:3840
	s_nop 0
	global_load_dwordx4 v[104:107], v[104:105], off offset:3968
.Lpf_skip:
	s_waitcnt lgkmcnt(0)
	ds_read_b128 v[136:139], v150
	ds_read_b128 v[140:143], v150 offset:64
	ds_read_b128 v[144:147], v160
	ds_read_b128 v[162:165], v160 offset:64
	s_waitcnt lgkmcnt(1)
	v_mfma_f32_16x16x32_bf16 v[144:147], v[136:139], v[144:147], 0
	v_lshl_add_u32 v215, v156, 2, s34
	v_lshl_add_u32 v216, v156, 3, s34
	s_waitcnt lgkmcnt(0)
	v_mfma_f32_16x16x32_bf16 v[144:147], v[140:143], v[162:165], v[144:147]
	ds_read_b128 v[162:165], v160 offset:2304
	ds_read_b128 v[166:169], v160 offset:2368
	s_waitcnt lgkmcnt(1)
	v_mfma_f32_16x16x32_bf16 v[162:165], v[136:139], v[162:165], 0
	s_waitcnt lgkmcnt(0)
	v_mfma_f32_16x16x32_bf16 v[162:165], v[140:143], v[166:169], v[162:165]
	ds_read_b128 v[166:169], v160 offset:4608
	ds_read_b128 v[170:173], v160 offset:4672
	s_waitcnt lgkmcnt(1)
	v_mfma_f32_16x16x32_bf16 v[166:169], v[136:139], v[166:169], 0
	s_waitcnt lgkmcnt(0)
	v_mfma_f32_16x16x32_bf16 v[166:169], v[140:143], v[170:173], v[166:169]
	ds_read_b128 v[170:173], v160 offset:6912
	ds_read_b128 v[174:177], v160 offset:6976
	s_waitcnt lgkmcnt(1)
	v_mfma_f32_16x16x32_bf16 v[136:139], v[136:139], v[170:173], 0
	ds_read_b128 v[170:173], v151
	s_nop 2
	v_cndmask_b32_e64 v144, v144, v166, s[0:1]
	v_add_f32_e32 v144, v124, v144
	s_waitcnt lgkmcnt(1)
	v_mfma_f32_16x16x32_bf16 v[136:139], v[140:143], v[174:177], v[136:139]
	ds_read_b128 v[140:143], v151 offset:64
	ds_read_b128 v[174:177], v160 offset:9216
	ds_read_b128 v[178:181], v160 offset:9280
	v_mul_f32_e32 v144, 0xbfb8aa3b, v144
	v_exp_f32_e32 v144, v144
	s_waitcnt lgkmcnt(1)
	v_mfma_f32_16x16x32_bf16 v[174:177], v[170:173], v[174:177], 0
	v_cndmask_b32_e64 v145, v145, v167, s[0:1]
	v_add_f32_e32 v144, 1.0, v144
	v_rcp_f32_e32 v144, v144
	s_waitcnt lgkmcnt(0)
	v_mfma_f32_16x16x32_bf16 v[174:177], v[140:143], v[178:181], v[174:177]
	ds_read_b128 v[178:181], v160 offset:11520
	ds_read_b128 v[184:187], v160 offset:11584
	v_add_f32_e32 v145, v124, v145
	v_mul_f32_e32 v144, 0xbf1b4598, v144
	s_waitcnt lgkmcnt(1)
	v_mfma_f32_16x16x32_bf16 v[178:181], v[170:173], v[178:181], 0
	v_mul_f32_e32 v144, 0x3fb8aa3b, v144
	v_mul_f32_e32 v145, 0xbfb8aa3b, v145
	v_exp_f32_e32 v144, v144
	s_waitcnt lgkmcnt(0)
	v_mfma_f32_16x16x32_bf16 v[178:181], v[140:143], v[184:187], v[178:181]
	ds_read_b128 v[184:187], v160 offset:13824
	ds_read_b128 v[188:191], v160 offset:13888
	v_exp_f32_e32 v145, v145
	v_cndmask_b32_e64 v147, v147, v169, s[0:1]
	s_waitcnt lgkmcnt(1)
	v_mfma_f32_16x16x32_bf16 v[184:187], v[170:173], v[184:187], 0
	v_cndmask_b32_e64 v146, v146, v168, s[0:1]
	v_lshl_add_u32 v169, v152, 2, s34
	v_cndmask_b32_e64 v136, v162, v136, s[0:1]
	s_waitcnt lgkmcnt(0)
	v_mfma_f32_16x16x32_bf16 v[184:187], v[140:143], v[188:191], v[184:187]
	ds_read_b128 v[188:191], v160 offset:16128
	ds_read_b128 v[192:195], v160 offset:16192
	v_add_f32_e32 v147, v124, v147
	v_add_f32_e32 v136, v125, v136
	s_waitcnt lgkmcnt(1)
	v_mfma_f32_16x16x32_bf16 v[170:173], v[170:173], v[188:191], 0
	s_nop 1
	v_cndmask_b32_e64 v167, v174, v184, s[0:1]
	v_add_f32_e32 v167, v126, v167
	v_mul_f32_e32 v167, 0xbfb8aa3b, v167
	v_exp_f32_e32 v167, v167
	v_mul_f32_e32 v147, 0xbfb8aa3b, v147
	v_mul_f32_e32 v136, 0xbfb8aa3b, v136
	s_waitcnt lgkmcnt(0)
	v_mfma_f32_16x16x32_bf16 v[140:143], v[140:143], v[192:195], v[170:173]
	v_add_f32_e32 v167, 1.0, v167
	v_rcp_f32_e32 v167, v167
	v_exp_f32_e32 v147, v147
	v_exp_f32_e32 v136, v136
	v_cndmask_b32_e64 v161, v177, v187, s[0:1]
	ds_write2st64_b32 v169, v144, v167 offset1:64
	v_mov_b32_e32 v252, v144
	v_add_f32_e32 v144, 1.0, v145
	v_add_f32_e32 v145, v124, v146
	v_mul_f32_e32 v145, 0xbfb8aa3b, v145
	v_exp_f32_e32 v145, v145
	v_cndmask_b32_e64 v166, v176, v186, s[0:1]
	v_cndmask_b32_e64 v168, v175, v185, s[0:1]
	v_add_f32_e32 v147, 1.0, v147
	v_add_f32_e32 v145, 1.0, v145
	v_cndmask_b32_e64 v137, v163, v137, s[0:1]
	v_add_f32_e32 v136, 1.0, v136
	v_cndmask_b32_e64 v140, v178, v140, s[0:1]
	v_rcp_f32_e32 v144, v144
	v_rcp_f32_e32 v145, v145
	v_add_f32_e32 v146, v126, v168
	v_add_f32_e32 v166, v126, v166
	v_rcp_f32_e32 v147, v147
	v_add_f32_e32 v161, v126, v161
	v_rcp_f32_e32 v136, v136
	v_add_f32_e32 v140, v127, v140
	v_add_f32_e32 v137, v125, v137
	v_mul_f32_e32 v146, 0xbfb8aa3b, v146
	v_mul_f32_e32 v166, 0xbfb8aa3b, v166
	v_mul_f32_e32 v161, 0xbfb8aa3b, v161
	v_mul_f32_e32 v140, 0xbfb8aa3b, v140
	v_mul_f32_e32 v137, 0xbfb8aa3b, v137
	v_exp_f32_e32 v146, v146
	v_exp_f32_e32 v166, v166
	v_exp_f32_e32 v161, v161
	v_exp_f32_e32 v140, v140
	v_exp_f32_e32 v137, v137
	v_mul_f32_e32 v144, 0xbf1b4598, v144
	v_mul_f32_e32 v145, 0xbf1b4598, v145
	v_mul_f32_e32 v147, 0xbf1b4598, v147
	v_mul_f32_e32 v136, 0xbf1b4598, v136
	v_mul_f32_e32 v144, 0x3fb8aa3b, v144
	v_mul_f32_e32 v145, 0x3fb8aa3b, v145
	v_mul_f32_e32 v147, 0x3fb8aa3b, v147
	v_mul_f32_e32 v136, 0x3fb8aa3b, v136
	v_exp_f32_e32 v144, v144
	v_exp_f32_e32 v145, v145
	v_add_f32_e32 v166, 1.0, v166
	v_exp_f32_e32 v147, v147
	v_add_f32_e32 v161, 1.0, v161
	v_add_f32_e32 v146, 1.0, v146
	v_exp_f32_e32 v136, v136
	v_add_f32_e32 v140, 1.0, v140
	v_add_f32_e32 v137, 1.0, v137
	v_rcp_f32_e32 v166, v166
	v_rcp_f32_e32 v161, v161
	v_rcp_f32_e32 v146, v146
	v_rcp_f32_e32 v140, v140
	v_rcp_f32_e32 v137, v137
	v_mul_f32_e32 v144, v144, v252
	v_mul_f32_e32 v145, v145, v144
	v_mul_f32_e32 v147, v147, v145
	v_mov_b32_e32 v253, v136
	ds_write2st64_b32 v169, v145, v147 offset0:2 offset1:3
	ds_write2st64_b32 v169, v166, v161 offset0:66 offset1:67
	v_cndmask_b32_e64 v138, v164, v138, s[0:1]
	ds_write2_b32 v169, v136, v144 offset0:16 offset1:64
	v_add_u32_e32 v136, 0x4000, v169
	v_cndmask_b32_e64 v139, v165, v139, s[0:1]
	ds_write2_b32 v136, v140, v146 offset0:16 offset1:64
	v_mul_f32_e32 v136, 0xbf1b4598, v137
	v_add_f32_e32 v137, v125, v138
	v_mul_f32_e32 v137, 0xbfb8aa3b, v137
	v_add_f32_e32 v139, v125, v139
	v_exp_f32_e32 v137, v137
	v_mul_f32_e32 v139, 0xbfb8aa3b, v139
	v_exp_f32_e32 v139, v139
	v_cndmask_b32_e64 v141, v179, v141, s[0:1]
	v_add_f32_e32 v137, 1.0, v137
	v_cndmask_b32_e64 v143, v181, v143, s[0:1]
	v_cndmask_b32_e64 v142, v180, v142, s[0:1]
	v_add_f32_e32 v138, v127, v141
	v_rcp_f32_e32 v137, v137
	v_add_f32_e32 v139, 1.0, v139
	v_mul_f32_e32 v138, 0xbfb8aa3b, v138
	v_add_f32_e32 v140, v127, v142
	v_rcp_f32_e32 v139, v139
	v_add_f32_e32 v141, v127, v143
	v_exp_f32_e32 v138, v138
	v_mul_f32_e32 v140, 0xbfb8aa3b, v140
	v_mul_f32_e32 v141, 0xbfb8aa3b, v141
	v_exp_f32_e32 v140, v140
	v_exp_f32_e32 v141, v141
	v_mul_f32_e32 v137, 0xbf1b4598, v137
	v_mul_f32_e32 v136, 0x3fb8aa3b, v136
	v_mul_f32_e32 v137, 0x3fb8aa3b, v137
	v_mul_f32_e32 v139, 0xbf1b4598, v139
	v_exp_f32_e32 v136, v136
	v_add_f32_e32 v138, 1.0, v138
	v_exp_f32_e32 v137, v137
	v_mul_f32_e32 v139, 0x3fb8aa3b, v139
	v_rcp_f32_e32 v138, v138
	v_add_f32_e32 v140, 1.0, v140
	v_exp_f32_e32 v139, v139
	v_add_f32_e32 v141, 1.0, v141
	v_rcp_f32_e32 v140, v140
	v_rcp_f32_e32 v141, v141
	v_lshl_add_u32 v142, v153, 2, s34
	v_mul_f32_e32 v136, v136, v253
	v_mul_f32_e32 v137, v137, v136
	v_mul_f32_e32 v139, v139, v137
	ds_write2st64_b32 v142, v136, v137 offset0:1 offset1:2
	ds_write2st64_b32 v142, v139, v138 offset0:3 offset1:65
	ds_write2st64_b32 v142, v140, v141 offset0:66 offset1:67
	s_waitcnt lgkmcnt(0)
	v_lshl_add_u32 v161, v154, 2, s34
	v_add_u32_e32 v254, 0xffffff00, v161
	ds_read_b128 v[228:231], v254
	ds_read_b128 v[232:235], v254 offset:16
	v_mbcnt_lo_u32_b32 v219, -1, 0
	v_mbcnt_hi_u32_b32 v219, -1, v219
	v_and_b32_e32 v217, 24, v219
	v_cmp_ne_u32_e64 s[44:45], 0, v217
	ds_read_b128 v[136:139], v161 offset:32768
	ds_read_b128 v[140:143], v161
	ds_read_b128 v[144:147], v161 offset:16
	ds_read_b128 v[162:165], v161 offset:32784
	s_add_i32 s34, s6, 3
	s_cmp_ge_u32 s34, s43
	s_waitcnt lgkmcnt(2)
	v_mul_f32_e32 v206, v136, v140
	v_mul_f32_e32 v207, v137, v141
	v_mul_f32_e32 v208, v138, v142
	v_mul_f32_e32 v209, v139, v143
	s_waitcnt lgkmcnt(0)
	v_mul_f32_e32 v210, v162, v144
	v_mul_f32_e32 v211, v163, v145
	v_mul_f32_e32 v212, v164, v146
	v_mul_f32_e32 v213, v165, v147
	v_rcp_f32_e32 v220, v140
	v_rcp_f32_e32 v221, v141
	v_rcp_f32_e32 v222, v142
	v_rcp_f32_e32 v223, v143
	v_rcp_f32_e32 v224, v144
	v_rcp_f32_e32 v225, v145
	v_rcp_f32_e32 v226, v146
	v_rcp_f32_e32 v227, v147
	v_cndmask_b32_e64 v228, 1.0, v228, s[44:45]
	v_cndmask_b32_e64 v229, 1.0, v229, s[44:45]
	v_cndmask_b32_e64 v230, 1.0, v230, s[44:45]
	v_cndmask_b32_e64 v231, 1.0, v231, s[44:45]
	v_cndmask_b32_e64 v232, 1.0, v232, s[44:45]
	v_cndmask_b32_e64 v233, 1.0, v233, s[44:45]
	v_cndmask_b32_e64 v234, 1.0, v234, s[44:45]
	v_cndmask_b32_e64 v235, 1.0, v235, s[44:45]
	ds_read_b128 v[140:143], v161 offset:16384
	ds_read_b128 v[144:147], v161 offset:16400
	ds_read_b128 v[166:169], v161 offset:24576
	ds_read_b128 v[170:173], v161 offset:24592
	s_waitcnt lgkmcnt(3)
	v_pk_add_f32 v[186:187], v[140:141], -1.0 op_sel_hi:[1,0]
	s_nop 0
	v_pk_fma_f32 v[186:187], v[28:29], v[186:187], 1.0 op_sel_hi:[1,1,0]
	s_waitcnt lgkmcnt(1)
	v_pk_mul_f32 v[184:185], v[20:21], v[166:167]
	v_pk_mul_f32 v[166:167], v[166:167], v[186:187]
	v_add_f32_e32 v187, -1.0, v142
	v_mov_b32_e32 v186, v168
	v_pk_mul_f32 v[198:199], v[22:23], v[186:187]
	v_add_f32_e32 v175, -1.0, v144
	s_waitcnt lgkmcnt(0)
	v_mov_b32_e32 v174, v170
	v_add_f32_e32 v191, -1.0, v143
	v_mov_b32_e32 v190, v169
	v_mov_b32_e32 v200, v184
	v_mov_b32_e32 v201, v198
	v_pk_mul_f32 v[176:177], v[24:25], v[174:175]
	v_pk_mul_f32 v[192:193], v[30:31], v[190:191]
	v_pk_mul_f32 v[200:201], v[200:201], v[200:201]
	v_mov_b32_e32 v188, v142
	v_mov_b32_e32 v194, v192
	v_mov_b32_e32 v195, v176
	v_fma_f32 v142, v185, v185, v200
	v_pk_mul_f32 v[194:195], v[194:195], v[194:195]
	v_add_f32_e32 v142, v142, v201
	v_add_f32_e32 v203, -1.0, v145
	v_mov_b32_e32 v202, v171
	v_add_f32_e32 v142, v142, v194
	v_pk_mul_f32 v[178:179], v[26:27], v[172:173]
	v_pk_mul_f32 v[204:205], v[32:33], v[202:203]
	v_add_f32_e32 v142, v142, v195
	v_pk_mul_f32 v[180:181], v[178:179], v[178:179]
	v_fmac_f32_e32 v142, v204, v204
	v_add_f32_e32 v142, v142, v180
	v_add_f32_e32 v142, v142, v181
	v_mov_b32_e32 v189, v168
	v_mov_b32_e32 v168, v143
	v_add_f32_dpp v142, v142, v142 quad_perm:[1,0,3,2] row_mask:0xf bank_mask:0xf bound_ctrl:1
	v_mov_b32_e32 v194, v144
	v_mul_f32_e32 v144, v137, v167
	v_add_f32_dpp v142, v142, v142 quad_perm:[2,3,0,1] row_mask:0xf bank_mask:0xf bound_ctrl:1
	v_mov_b32_e32 v180, v139
	v_mov_b32_e32 v195, v170
	v_add_f32_dpp v142, v142, v142 row_half_mirror row_mask:0xf bank_mask:0xf bound_ctrl:1
	v_max_f32_e32 v142, 0x179abe15, v142
	v_rsq_f32_e32 v182, v142
	v_mov_b32_e32 v170, v145
	v_mov_b32_e32 v145, v172
	v_mov_b32_e32 v172, v147
	v_pk_mul_f32 v[142:143], v[184:185], v[182:183] op_sel_hi:[1,0]
	v_mov_b32_e32 v185, v166
	v_pk_mul_f32 v[140:141], v[140:141], v[142:143]
	v_xor_b32_e32 v181, 0x80000000, v142
	v_mov_b32_e32 v184, v140
	v_mul_f32_e32 v142, v136, v166
	v_fma_f32 v200, v36, v142, 0
	v_pk_fma_f32 v[184:185], v[136:137], v[184:185], 0 op_sel_hi:[0,1,0]
	v_xor_b32_e32 v201, 0x80000000, v143
	v_mov_b32_e32 v142, v141
	v_mov_b32_e32 v143, v167
	v_pk_fma_f32 v[136:137], v[136:137], v[142:143], v[184:185] op_sel:[1,0,0]
	v_pk_mul_f32 v[142:143], v[198:199], v[182:183]
	v_pk_fma_f32 v[184:185], v[22:23], v[186:187], s[2:3]
	v_fmac_f32_e32 v200, v37, v144
	v_mov_b32_e32 v143, v185
	v_pk_mul_f32 v[184:185], v[188:189], v[142:143]
	v_xor_b32_e32 v188, 0x80000000, v142
	v_mul_f32_e32 v142, v185, v138
	v_fmac_f32_e32 v200, v38, v142
	v_pk_mul_f32 v[142:143], v[192:193], v[182:183]
	v_pk_fma_f32 v[186:187], v[30:31], v[190:191], s[2:3]
	v_pk_fma_f32 v[136:137], v[184:185], v[138:139], v[136:137] op_sel_hi:[1,0,1]
	v_mov_b32_e32 v143, v187
	v_pk_mul_f32 v[186:187], v[168:169], v[142:143]
	v_xor_b32_e32 v189, 0x80000000, v142
	v_mov_b32_e32 v142, v184
	v_mov_b32_e32 v143, v186
	v_mul_f32_e32 v138, v187, v139
	v_pk_mul_f32 v[236:237], v[140:141], v[220:221]
	v_pk_mul_f32 v[238:239], v[142:143], v[222:223]
	ds_write_b128 v161, v[236:239] offset:16384
	v_fmac_f32_e32 v200, v39, v138
	v_pk_mul_f32 v[138:139], v[176:177], v[182:183]
	v_pk_fma_f32 v[140:141], v[24:25], v[174:175], s[2:3]
	v_mov_b32_e32 v168, v185
	v_mov_b32_e32 v139, v141
	v_mov_b32_e32 v169, v187
	v_pk_mul_f32 v[142:143], v[194:195], v[138:139]
	v_pk_mul_f32 v[240:241], v[166:167], v[220:221]
	v_pk_mul_f32 v[242:243], v[168:169], v[222:223]
	ds_write_b128 v161, v[240:243] offset:24576
	v_pk_fma_f32 v[136:137], v[186:187], v[180:181], v[136:137] op_sel_hi:[1,0,1]
	v_xor_b32_e32 v166, 0x80000000, v138
	v_mul_f32_e32 v138, v143, v162
	v_fmac_f32_e32 v200, v40, v138
	v_pk_fma_f32 v[138:139], v[142:143], v[162:163], v[136:137] op_sel_hi:[1,0,1]
	v_pk_mul_f32 v[140:141], v[204:205], v[182:183]
	v_pk_fma_f32 v[136:137], v[32:33], v[202:203], s[2:3]
	v_xor_b32_e32 v167, 0x80000000, v140
	v_mov_b32_e32 v141, v137
	v_pk_mul_f32 v[136:137], v[170:171], v[140:141]
	v_mul_f32_e64 v168, v178, -v182
	v_mul_f32_e32 v140, v137, v163
	v_fmac_f32_e32 v200, v41, v140
	v_add_f32_e32 v140, -1.0, v146
	v_fma_f32 v141, v34, v140, 1.0
	v_mov_b32_e32 v144, v146
	v_xor_b32_e32 v140, 0x80000000, v168
	v_pk_fma_f32 v[138:139], v[136:137], v[162:163], v[138:139] op_sel:[0,1,0]
	v_pk_mul_f32 v[144:145], v[144:145], v[140:141]
	s_nop 0
	v_mul_f32_e32 v140, v145, v164
	v_pk_fma_f32 v[162:163], v[144:145], v[164:165], v[138:139] op_sel_hi:[1,0,1]
	v_add_f32_e32 v138, -1.0, v147
	v_mul_f32_e64 v164, v179, -v182
	v_fma_f32 v139, v35, v138, 1.0
	v_xor_b32_e32 v138, 0x80000000, v164
	v_pk_mul_f32 v[146:147], v[172:173], v[138:139]
	v_fmac_f32_e32 v200, v42, v140
	v_mov_b32_e32 v138, v142
	v_mov_b32_e32 v139, v136
	v_mov_b32_e32 v140, v144
	v_mov_b32_e32 v141, v146
	v_pk_mul_f32 v[244:245], v[138:139], v[224:225]
	v_pk_mul_f32 v[246:247], v[140:141], v[226:227]
	ds_write_b128 v161, v[244:247] offset:16400
	v_mov_b32_e32 v136, v143
	v_mov_b32_e32 v138, v145
	v_mov_b32_e32 v139, v147
	v_pk_mul_f32 v[248:249], v[136:137], v[224:225]
	v_pk_mul_f32 v[250:251], v[138:139], v[226:227]
	ds_write_b128 v161, v[248:251] offset:24592
	v_mov_b32_e32 v136, v165
	v_mul_f32_e32 v137, v147, v165
	v_fmac_f32_e32 v200, v43, v137
	v_pk_fma_f32 v[144:145], v[146:147], v[136:137], v[162:163] op_sel_hi:[1,0,1]
	v_mul_f32_e32 v228, v181, v228
	v_mul_f32_e32 v229, v201, v229
	v_cvt_pk_bf16_f32 v136, v228, v229
	v_mul_f32_e32 v230, v188, v230
	v_mul_f32_e32 v231, v189, v231
	v_cvt_pk_bf16_f32 v137, v230, v231
	v_mul_f32_e32 v232, v166, v232
	v_mul_f32_e32 v233, v167, v233
	v_cvt_pk_bf16_f32 v138, v232, v233
	v_mul_f32_e32 v234, v168, v234
	v_mul_f32_e32 v235, v164, v235
	v_cvt_pk_bf16_f32 v139, v234, v235
	v_cvt_pk_bf16_f32 v140, v206, v207
	v_cvt_pk_bf16_f32 v141, v208, v209
	v_cvt_pk_bf16_f32 v142, v210, v211
	v_cvt_pk_bf16_f32 v143, v212, v213
	ds_write_b128 v214, v[136:139] offset:8192
	ds_write_b128 v214, v[140:143] offset:12288
	v_add_f32_dpp v136, v200, v200 quad_perm:[1,0,3,2] row_mask:0xf bank_mask:0xf bound_ctrl:1
	v_mov_b32_dpp v137, v145 quad_perm:[1,0,3,2] row_mask:0xf bank_mask:0xf bound_ctrl:1
	s_nop 0
	v_add_f32_dpp v136, v136, v136 quad_perm:[2,3,0,1] row_mask:0xf bank_mask:0xf bound_ctrl:1
	s_nop 1
	v_add_f32_dpp v140, v136, v136 row_half_mirror row_mask:0xf bank_mask:0xf bound_ctrl:1
	v_mov_b32_dpp v136, v144 quad_perm:[1,0,3,2] row_mask:0xf bank_mask:0xf bound_ctrl:1
	v_pk_add_f32 v[136:137], v[144:145], v[136:137]
	ds_write_b32 v215, v140 offset:57216
	s_nop 0
	v_mov_b32_dpp v138, v136 quad_perm:[2,3,0,1] row_mask:0xf bank_mask:0xf bound_ctrl:1
	v_mov_b32_dpp v139, v137 quad_perm:[2,3,0,1] row_mask:0xf bank_mask:0xf bound_ctrl:1
	v_pk_add_f32 v[136:137], v[136:137], v[138:139]
	s_nop 1
	v_mov_b32_dpp v138, v136 row_half_mirror row_mask:0xf bank_mask:0xf bound_ctrl:1
; #define PREFETCH(ch_) do { const size_t rb_ = row0 + (size_t)(ch_) * 32 + tA; \
;       _Pragma("unroll") for (int seg = 0; seg < 5; ++seg) { \
;         cur[seg] = *(const u32x4*)(PS + rb_ * 3200 + PS_COL(seg)); \
;         if ((ch_) > 0 || tA > 0) prv[seg] = *(const u32x4*)(PS + (rb_ - 1) * 3200 + PS_COL(seg)); } } while (0)
; DI void scan_item(const Params& p, char* smem, int b, int h, bool prompt, const int g_wave) {
;     ...
;       if (k + 1 < nch) {
;         PREP_ABC(k + 1);
;         if (k + 2 < nch) PREFETCH(k + 2);
;       }
;       asm volatile("s_waitcnt lgkmcnt(0)" ::: "memory");
;       __builtin_amdgcn_s_barrier();
;       asm volatile("" ::: "memory");
;     }
	v_mov_b32_dpp v139, v137 row_half_mirror row_mask:0xf bank_mask:0xf bound_ctrl:1
	v_pk_add_f32 v[136:137], v[136:137], v[138:139]
	ds_write_b64 v216, v[136:137] offset:57216
	v_mul_f32_dpp v220, v236, v228 row_shr:8 row_mask:0xf bank_mask:0xf bound_ctrl:1
	v_mul_f32_dpp v221, v240, v228 row_shr:8 row_mask:0xf bank_mask:0xf bound_ctrl:1
	v_mul_f32_dpp v222, v236, v206 row_shr:8 row_mask:0xf bank_mask:0xf bound_ctrl:1
	v_mul_f32_dpp v223, v240, v206 row_shr:8 row_mask:0xf bank_mask:0xf bound_ctrl:1
	v_fmac_f32_dpp v220, v237, v229 row_shr:8 row_mask:0xf bank_mask:0xf bound_ctrl:1
	v_fmac_f32_dpp v221, v241, v229 row_shr:8 row_mask:0xf bank_mask:0xf bound_ctrl:1
	v_fmac_f32_dpp v222, v237, v207 row_shr:8 row_mask:0xf bank_mask:0xf bound_ctrl:1
	v_fmac_f32_dpp v223, v241, v207 row_shr:8 row_mask:0xf bank_mask:0xf bound_ctrl:1
	v_fmac_f32_dpp v220, v238, v230 row_shr:8 row_mask:0xf bank_mask:0xf bound_ctrl:1
	v_fmac_f32_dpp v221, v242, v230 row_shr:8 row_mask:0xf bank_mask:0xf bound_ctrl:1
	v_fmac_f32_dpp v222, v238, v208 row_shr:8 row_mask:0xf bank_mask:0xf bound_ctrl:1
	v_fmac_f32_dpp v223, v242, v208 row_shr:8 row_mask:0xf bank_mask:0xf bound_ctrl:1
	v_fmac_f32_dpp v220, v239, v231 row_shr:8 row_mask:0xf bank_mask:0xf bound_ctrl:1
	v_fmac_f32_dpp v221, v243, v231 row_shr:8 row_mask:0xf bank_mask:0xf bound_ctrl:1
	v_fmac_f32_dpp v222, v239, v209 row_shr:8 row_mask:0xf bank_mask:0xf bound_ctrl:1
	v_fmac_f32_dpp v223, v243, v209 row_shr:8 row_mask:0xf bank_mask:0xf bound_ctrl:1
	v_fmac_f32_dpp v220, v244, v232 row_shr:8 row_mask:0xf bank_mask:0xf bound_ctrl:1
	v_fmac_f32_dpp v221, v248, v232 row_shr:8 row_mask:0xf bank_mask:0xf bound_ctrl:1
	v_fmac_f32_dpp v222, v244, v210 row_shr:8 row_mask:0xf bank_mask:0xf bound_ctrl:1
	v_fmac_f32_dpp v223, v248, v210 row_shr:8 row_mask:0xf bank_mask:0xf bound_ctrl:1
	v_fmac_f32_dpp v220, v245, v233 row_shr:8 row_mask:0xf bank_mask:0xf bound_ctrl:1
	v_fmac_f32_dpp v221, v249, v233 row_shr:8 row_mask:0xf bank_mask:0xf bound_ctrl:1
	v_fmac_f32_dpp v222, v245, v211 row_shr:8 row_mask:0xf bank_mask:0xf bound_ctrl:1
	v_fmac_f32_dpp v223, v249, v211 row_shr:8 row_mask:0xf bank_mask:0xf bound_ctrl:1
	v_fmac_f32_dpp v220, v246, v234 row_shr:8 row_mask:0xf bank_mask:0xf bound_ctrl:1
	v_fmac_f32_dpp v221, v250, v234 row_shr:8 row_mask:0xf bank_mask:0xf bound_ctrl:1
	v_fmac_f32_dpp v222, v246, v212 row_shr:8 row_mask:0xf bank_mask:0xf bound_ctrl:1
	v_fmac_f32_dpp v223, v250, v212 row_shr:8 row_mask:0xf bank_mask:0xf bound_ctrl:1
	v_fmac_f32_dpp v220, v247, v235 row_shr:8 row_mask:0xf bank_mask:0xf bound_ctrl:1
	v_fmac_f32_dpp v221, v251, v235 row_shr:8 row_mask:0xf bank_mask:0xf bound_ctrl:1
	v_fmac_f32_dpp v222, v247, v213 row_shr:8 row_mask:0xf bank_mask:0xf bound_ctrl:1
	v_fmac_f32_dpp v223, v251, v213 row_shr:8 row_mask:0xf bank_mask:0xf bound_ctrl:1
	v_add_f32_dpp v220, v220, v220 quad_perm:[1,0,3,2] row_mask:0xf bank_mask:0xf bound_ctrl:1
	v_add_f32_dpp v221, v221, v221 quad_perm:[1,0,3,2] row_mask:0xf bank_mask:0xf bound_ctrl:1
	v_add_f32_dpp v222, v222, v222 quad_perm:[1,0,3,2] row_mask:0xf bank_mask:0xf bound_ctrl:1
	v_add_f32_dpp v223, v223, v223 quad_perm:[1,0,3,2] row_mask:0xf bank_mask:0xf bound_ctrl:1
	v_add_f32_dpp v220, v220, v220 quad_perm:[2,3,0,1] row_mask:0xf bank_mask:0xf bound_ctrl:1
	v_add_f32_dpp v221, v221, v221 quad_perm:[2,3,0,1] row_mask:0xf bank_mask:0xf bound_ctrl:1
	v_add_f32_dpp v222, v222, v222 quad_perm:[2,3,0,1] row_mask:0xf bank_mask:0xf bound_ctrl:1
	v_add_f32_dpp v223, v223, v223 quad_perm:[2,3,0,1] row_mask:0xf bank_mask:0xf bound_ctrl:1
	v_add_f32_dpp v220, v220, v220 row_half_mirror row_mask:0xf bank_mask:0xf bound_ctrl:1
	v_add_f32_dpp v221, v221, v221 row_half_mirror row_mask:0xf bank_mask:0xf bound_ctrl:1
	v_add_f32_dpp v222, v222, v222 row_half_mirror row_mask:0xf bank_mask:0xf bound_ctrl:1
	v_add_f32_dpp v223, v223, v223 row_half_mirror row_mask:0xf bank_mask:0xf bound_ctrl:1
	v_cmp_lt_u32_e32 vcc, 0x7530, v161
	v_lshrrev_b32_e32 v217, 7, v154
	v_lshlrev_b32_e32 v217, 4, v217
	v_not_b32_e32 v254, v219
	v_and_b32_e32 v254, 8, v254
	v_lshlrev_b32_e32 v254, 7, v254
	v_mov_b32_e32 v224, 0x100
	v_cndmask_b32_e32 v224, 0, v224, vcc
	v_add3_u32 v217, v217, v254, v224
	v_add_u32_e32 v217, 0x24010, v217
	ds_write_b128 v217, v[220:223]
	s_branch .LBB0_784
